# up GEMM epilogue: rowss loads issued at tile start; packed outputs lane-transposed (ds_bpermute) so 4 adjacent lanes store a contiguous 64B row segment
# speedup vs baseline: 1.0122x; 1.0055x over previous
; __device__ __forceinline__ float ss_rinv(u64 v) { return __builtin_amdgcn_rsqf((float)v * SS_INV + 1e-6f); }
;     __host__ __device__ bool next(int i, Unit& u) const {
;         const long L = (long)i * G + c; if (L >= nwg) return false;
;         u.ks = 0;
;         if (KS > 1) { const int l = (int)L; u.ks = l % KS; const int t = l / KS; u.pm = t % nM; u.pn = t / nM; return true; }
;         int wgid = (int)L; { const int q = nwg / NXCD, r = nwg % NXCD, xcd = wgid % NXCD, off = wgid / NXCD; wgid = (xcd < r ? xcd * (q + 1) : r * (q + 1) + (xcd - r) * q) + off; }
;         const int nig = WGM * nN, gid = wgid / nig, fm = gid * WGM, gsz = (nM - fm) < WGM ? (nM - fm) : WGM;
;         u.pm = fm + ((wgid % nig) % gsz); u.pn = (wgid % nig) / gsz; return true;
;     }
;     __device__ __forceinline__ void operator()(const f32x4 (&acc)[2][2][4][2], const pg8::Unit& u, int wr, int wc, int fr, int fq) const {
;     ...
;                 const int lrow = u.pm * 256 + ai * 128 + wr * 64 + m * 16 + fr, grow = row_base + lrow;
;                 if (grow >= MREAL) continue;
;                 const float ri = ss_rinv(rowss[grow]);
.LBB0_2029:
	v_lshl_add_u32 v248, s38, 8, v158
	v_add_u32_e32 v248, s66, v248
	v_ashrrev_i32_e32 v249, 31, v248
	v_lshl_add_u64 v[246:247], v[248:249], 3, s[12:13]
	global_load_dwordx2 v[230:231], v[246:247], off
	global_load_dwordx2 v[232:233], v[246:247], off offset:128
	global_load_dwordx2 v[234:235], v[246:247], off offset:256
	global_load_dwordx2 v[236:237], v[246:247], off offset:384
	global_load_dwordx2 v[238:239], v[246:247], off offset:1024
	global_load_dwordx2 v[240:241], v[246:247], off offset:1152
	global_load_dwordx2 v[242:243], v[246:247], off offset:1280
	global_load_dwordx2 v[244:245], v[246:247], off offset:1408
	s_add_i32 s77, s77, 1
	s_mul_i32 s2, s77, s74
	s_mul_hi_u32 s3, s77, s47
	s_add_i32 s3, s3, s2
	s_mul_i32 s2, s77, s47
	s_add_u32 s30, s2, s48
	s_addc_u32 s31, s3, s75
	v_mov_b64_e32 v[0:1], s[56:57]
	v_cmp_ge_i64_e32 vcc, s[30:31], v[0:1]
	v_cmp_lt_i64_e64 s[2:3], s[30:31], v[0:1]
	s_cbranch_vccnz .LBB0_2031
	s_ashr_i32 s26, s30, 31
	s_lshr_b32 s26, s26, 29
	s_add_i32 s26, s30, s26
	s_ashr_i32 s27, s26, 3
	s_and_b32 s26, s26, -8
	s_sub_i32 s26, s30, s26
	v_mov_b32_e32 v0, s26
	v_alignbit_b32 v0, s46, v0, 31
	s_nop 0
	v_readfirstlane_b32 s28, v0
	s_mul_i32 s26, s28, s26
	s_add_i32 s26, s26, s27
	s_ashr_i32 s27, s26, 31
	s_lshr_b32 s27, s27, 25
	s_add_i32 s27, s26, s27
	s_ashr_i32 s28, s27, 7
	s_lshl_b32 s28, s28, 3
	s_sub_i32 s29, s46, s28
	s_min_i32 s29, s29, 8
	s_abs_i32 s30, s29
	v_cvt_f32_u32_e32 v0, s30
	s_sub_i32 s34, 0, s30
	s_and_b32 s27, s27, 0xffffff80
	s_sub_i32 s27, s26, s27
	v_rcp_iflag_f32_e32 v0, v0
	s_abs_i32 s26, s27
	s_xor_b32 s31, s27, s29
	s_ashr_i32 s31, s31, 31
	v_mul_f32_e32 v0, 0x4f7ffffe, v0
	v_cvt_u32_f32_e32 v0, v0
	s_nop 0
	v_readfirstlane_b32 s35, v0
	s_mul_i32 s34, s34, s35
	s_mul_hi_u32 s34, s35, s34
	s_add_i32 s35, s35, s34
	s_mul_hi_u32 s34, s26, s35
	s_mul_i32 s35, s34, s30
	s_sub_i32 s26, s26, s35
	s_add_i32 s37, s34, 1
	s_sub_i32 s35, s26, s30
	s_cmp_ge_u32 s26, s30
	s_cselect_b32 s34, s37, s34
	s_cselect_b32 s26, s35, s26
	s_add_i32 s35, s34, 1
	s_cmp_ge_u32 s26, s30
	s_cselect_b32 s26, s35, s34
	s_xor_b32 s26, s26, s31
	s_sub_i32 s26, s26, s31
	s_mul_i32 s29, s26, s29
	s_sub_i32 s27, s27, s29
	s_add_i32 s28, s27, s28

; #define PG8_STAGE(bufoff, gbase, voff) do { _Pragma("unroll") for (int _i = 0; _i < 2; ++_i) \
;         __builtin_amdgcn_global_load_lds((const unsigned*)((const char*)(gbase) + (voff)[_i]), (PG8_LAS unsigned*)(lds + (bufoff) + ldsw + _i * 8192), 16, 0, 0); } while (0)
; #define PG8_LDA(dst, b, h) do { _Pragma("unroll") for (int m = 0; m < 4; ++m) _Pragma("unroll") for (int k = 0; k < 2; ++k) dst[m][k] = *(const PG8_LAS bf16x8*)(lds + PG8_SA(b, h) + aoff + m * 2048 + k * 1024); } while (0)
; #define PG8_LDB(dst, b, h) do { _Pragma("unroll") for (int n = 0; n < 2; ++n) _Pragma("unroll") for (int k = 0; k < 2; ++k) dst[n][k] = *(const PG8_LAS bf16x8*)(lds + PG8_SB(b, h) + boff + n * 2048 + k * 1024); } while (0)
; #define PG8_WAIT_V(n) asm volatile("s_waitcnt vmcnt(" #n ")" ::: "memory")
; #define PG8_WAIT_L(n) asm volatile("s_waitcnt lgkmcnt(" #n ")" ::: "memory")
; #define PG8_BAR __builtin_amdgcn_s_barrier()
; #define PG8_SCHED __builtin_amdgcn_sched_barrier(0)
; template <class Epi, bool ALIGN_EPI = true>
; __device__ __forceinline__ void gemm_phase(PG8_LAS unsigned char* lds, const Gemm g, const StaticOrder& S, const Epi& E) {
;     ...
;             PG8_LDB(B0, 0, 0); PG8_LDB(B1, 0, 1); PG8_SCHED; PG8_LDA(At, 0, 0); PG8_STAGE(PG8_SA(1, 1), a1 + hstepA, voffA);
;             PG8_WAIT_V(8); PG8_WAIT_L(0); PG8_BAR; PG8_MMA(0, 0, At, B0); PG8_MMA(0, 1, At, B1); PG8_BAR; PG8_SCHED;
;             PG8_LDA(At, 0, 1); PG8_STAGE(PG8_SB(0, 0), b2, voffB); PG8_STAGE(PG8_SB(0, 1), b2 + hstepB, voffB); PG8_STAGE(PG8_SA(0, 0), a2, voffA);
;             PG8_WAIT_V(8); PG8_WAIT_L(0); PG8_BAR; PG8_MMA(1, 0, At, B0); PG8_MMA(1, 1, At, B1); PG8_BAR; PG8_SCHED;
.LBB0_2032:
	s_add_u32 s42, s40, 0xfffc0080
	s_addc_u32 s43, s41, -1
	s_add_i32 s87, 0, 0x10000
	s_cmp_eq_u32 s86, 12
	s_cselect_b32 s45, s29, s43
	s_cselect_b32 s44, s37, s42
	v_add_u32_e32 v144, s87, v159
	s_cselect_b32 s43, s27, s85
	s_cselect_b32 s42, s82, s83
	s_add_i32 s90, 0, 0x14000
	ds_read_b128 v[140:143], v144
	ds_read_b128 v[148:151], v144 offset:1024
	ds_read_b128 v[162:165], v144 offset:2048
	ds_read_b128 v[166:169], v144 offset:3072
	v_add_u32_e32 v144, s90, v159
	ds_read_b128 v[170:173], v144
	ds_read_b128 v[174:177], v144 offset:1024
	ds_read_b128 v[178:181], v144 offset:2048
	ds_read_b128 v[182:185], v144 offset:3072
	v_lshl_add_u64 v[144:145], s[40:41], 0, v[136:137]
	s_add_i32 m0, s39, 0xc000
	ds_read_b128 v[186:189], v161
	ds_read_b128 v[190:193], v161 offset:1024
	ds_read_b128 v[194:197], v161 offset:2048
	ds_read_b128 v[198:201], v161 offset:3072
	ds_read_b128 v[208:211], v161 offset:4096
	ds_read_b128 v[216:219], v161 offset:5120
	ds_read_b128 v[220:223], v161 offset:6144
	ds_read_b128 v[224:227], v161 offset:7168
	global_load_lds_dwordx4 v[144:145], off
	v_lshl_add_u64 v[144:145], s[40:41], 0, v[138:139]
	s_add_i32 m0, s39, 0xe000
	s_nop 0
	global_load_lds_dwordx4 v[144:145], off
	s_waitcnt vmcnt(16)
	s_waitcnt lgkmcnt(0)
	s_barrier
	s_setprio 1
	s_waitcnt lgkmcnt(0)
	v_mfma_f32_16x16x32_bf16 v[126:129], v[140:143], v[186:189], 0
	v_mfma_f32_16x16x32_bf16 v[122:125], v[162:165], v[186:189], 0
	v_mfma_f32_16x16x32_bf16 v[110:113], v[140:143], v[194:197], 0
	v_mfma_f32_16x16x32_bf16 v[106:109], v[162:165], v[194:197], 0
	v_mfma_f32_16x16x32_bf16 v[94:97], v[140:143], v[208:211], 0
	v_mfma_f32_16x16x32_bf16 v[90:93], v[162:165], v[208:211], 0
	v_mfma_f32_16x16x32_bf16 v[78:81], v[140:143], v[220:223], 0
	v_mfma_f32_16x16x32_bf16 v[74:77], v[162:165], v[220:223], 0
	v_mfma_f32_16x16x32_bf16 v[126:129], v[148:151], v[190:193], v[126:129]
	v_mfma_f32_16x16x32_bf16 v[122:125], v[166:169], v[190:193], v[122:125]
	v_mfma_f32_16x16x32_bf16 v[110:113], v[148:151], v[198:201], v[110:113]
	v_mfma_f32_16x16x32_bf16 v[106:109], v[166:169], v[198:201], v[106:109]
	v_mfma_f32_16x16x32_bf16 v[94:97], v[148:151], v[216:219], v[94:97]
	v_mfma_f32_16x16x32_bf16 v[90:93], v[166:169], v[216:219], v[90:93]
	v_mfma_f32_16x16x32_bf16 v[78:81], v[148:151], v[224:227], v[78:81]
	v_mfma_f32_16x16x32_bf16 v[74:77], v[166:169], v[224:227], v[74:77]
	v_mfma_f32_16x16x32_bf16 v[118:121], v[170:173], v[186:189], 0
	v_mfma_f32_16x16x32_bf16 v[114:117], v[178:181], v[186:189], 0
	v_mfma_f32_16x16x32_bf16 v[102:105], v[170:173], v[194:197], 0
	v_mfma_f32_16x16x32_bf16 v[98:101], v[178:181], v[194:197], 0
	v_mfma_f32_16x16x32_bf16 v[86:89], v[170:173], v[208:211], 0
	v_mfma_f32_16x16x32_bf16 v[82:85], v[178:181], v[208:211], 0
	v_mfma_f32_16x16x32_bf16 v[70:73], v[170:173], v[220:223], 0
	v_mfma_f32_16x16x32_bf16 v[66:69], v[178:181], v[220:223], 0
	v_mfma_f32_16x16x32_bf16 v[118:121], v[174:177], v[190:193], v[118:121]
	v_mfma_f32_16x16x32_bf16 v[114:117], v[182:185], v[190:193], v[114:117]
	v_mfma_f32_16x16x32_bf16 v[102:105], v[174:177], v[198:201], v[102:105]
	v_mfma_f32_16x16x32_bf16 v[98:101], v[182:185], v[198:201], v[98:101]
	v_mfma_f32_16x16x32_bf16 v[86:89], v[174:177], v[216:219], v[86:89]
	v_mfma_f32_16x16x32_bf16 v[82:85], v[182:185], v[216:219], v[82:85]
	v_mfma_f32_16x16x32_bf16 v[70:73], v[174:177], v[224:227], v[70:73]
	v_mfma_f32_16x16x32_bf16 v[66:69], v[182:185], v[224:227], v[66:69]
	s_setprio 0
	s_barrier
	s_add_i32 s87, s87, s53
	v_lshl_add_u64 v[144:145], s[42:43], 0, v[32:33]
	s_mov_b32 m0, s87
	ds_read_b128 v[186:189], v161 offset:16384
	ds_read_b128 v[190:193], v161 offset:17408
	ds_read_b128 v[194:197], v161 offset:18432
	ds_read_b128 v[198:201], v161 offset:19456
	ds_read_b128 v[208:211], v161 offset:20480
	ds_read_b128 v[216:219], v161 offset:21504
	ds_read_b128 v[220:223], v161 offset:22528
	ds_read_b128 v[224:227], v161 offset:23552
	global_load_lds_dwordx4 v[144:145], off
	s_add_i32 m0, s87, 0x2000
	s_add_u32 s88, s42, 0x40000
	v_lshl_add_u64 v[146:147], s[42:43], 0, v[134:135]
	s_addc_u32 s89, s43, 0
	s_add_i32 s87, s90, s53
	global_load_lds_dwordx4 v[146:147], off
	v_lshl_add_u64 v[204:205], s[88:89], 0, v[32:33]
	s_mov_b32 m0, s87
	v_lshl_add_u64 v[206:207], s[44:45], 0, v[132:133]
	global_load_lds_dwordx4 v[204:205], off
	v_lshl_add_u64 v[204:205], s[88:89], 0, v[134:135]
	s_add_i32 m0, s87, 0x2000
	s_nop 0
	global_load_lds_dwordx4 v[204:205], off
	v_lshl_add_u64 v[204:205], s[44:45], 0, v[130:131]
	s_mov_b32 m0, s39
	s_nop 0
	global_load_lds_dwordx4 v[204:205], off
	s_mov_b32 m0, s67
	s_nop 0
	global_load_lds_dwordx4 v[206:207], off
	s_waitcnt vmcnt(16)
	s_waitcnt lgkmcnt(0)
	s_barrier
	s_setprio 1
	s_waitcnt lgkmcnt(0)
	v_mfma_f32_16x16x32_bf16 v[62:65], v[140:143], v[186:189], 0
	v_mfma_f32_16x16x32_bf16 v[58:61], v[162:165], v[186:189], 0
	v_mfma_f32_16x16x32_bf16 v[46:49], v[140:143], v[194:197], 0
	v_mfma_f32_16x16x32_bf16 v[42:45], v[162:165], v[194:197], 0
	v_mfma_f32_16x16x32_bf16 v[28:31], v[140:143], v[208:211], 0
	v_mfma_f32_16x16x32_bf16 v[24:27], v[162:165], v[208:211], 0
	v_mfma_f32_16x16x32_bf16 v[12:15], v[140:143], v[220:223], 0
	v_mfma_f32_16x16x32_bf16 v[8:11], v[162:165], v[220:223], 0
	v_mfma_f32_16x16x32_bf16 v[62:65], v[148:151], v[190:193], v[62:65]
	v_mfma_f32_16x16x32_bf16 v[58:61], v[166:169], v[190:193], v[58:61]
	v_mfma_f32_16x16x32_bf16 v[46:49], v[148:151], v[198:201], v[46:49]
	v_mfma_f32_16x16x32_bf16 v[42:45], v[166:169], v[198:201], v[42:45]
	v_mfma_f32_16x16x32_bf16 v[28:31], v[148:151], v[216:219], v[28:31]
	v_mfma_f32_16x16x32_bf16 v[24:27], v[166:169], v[216:219], v[24:27]
	v_mfma_f32_16x16x32_bf16 v[12:15], v[148:151], v[224:227], v[12:15]
	v_mfma_f32_16x16x32_bf16 v[8:11], v[166:169], v[224:227], v[8:11]
	v_mfma_f32_16x16x32_bf16 v[54:57], v[170:173], v[186:189], 0
	v_mfma_f32_16x16x32_bf16 v[50:53], v[178:181], v[186:189], 0
	v_mfma_f32_16x16x32_bf16 v[38:41], v[170:173], v[194:197], 0
	v_mfma_f32_16x16x32_bf16 v[34:37], v[178:181], v[194:197], 0
	v_mfma_f32_16x16x32_bf16 v[20:23], v[170:173], v[208:211], 0
	v_mfma_f32_16x16x32_bf16 v[16:19], v[178:181], v[208:211], 0
	v_mfma_f32_16x16x32_bf16 v[4:7], v[170:173], v[220:223], 0
	v_mfma_f32_16x16x32_bf16 v[0:3], v[178:181], v[220:223], 0
	v_mfma_f32_16x16x32_bf16 v[54:57], v[174:177], v[190:193], v[54:57]
	v_mfma_f32_16x16x32_bf16 v[50:53], v[182:185], v[190:193], v[50:53]
	v_mfma_f32_16x16x32_bf16 v[38:41], v[174:177], v[198:201], v[38:41]
	v_mfma_f32_16x16x32_bf16 v[34:37], v[182:185], v[198:201], v[34:37]
	v_mfma_f32_16x16x32_bf16 v[20:23], v[174:177], v[216:219], v[20:23]
	v_mfma_f32_16x16x32_bf16 v[16:19], v[182:185], v[216:219], v[16:19]
	v_mfma_f32_16x16x32_bf16 v[4:7], v[174:177], v[224:227], v[4:7]
	v_mfma_f32_16x16x32_bf16 v[0:3], v[182:185], v[224:227], v[0:3]
	s_setprio 0
	s_barrier
	s_branch .Lp3_2032

; __device__ __forceinline__ float ss_rinv(u64 v) { return __builtin_amdgcn_rsqf((float)v * SS_INV + 1e-6f); }
; __device__ __forceinline__ unsigned cvtpk(float lo, float hi) { f32x2 v = {lo, hi}; bf16x2_t b = __builtin_convertvector(v, bf16x2_t); return __builtin_bit_cast(unsigned, b); }
;     __device__ __forceinline__ void operator()(const f32x4 (&acc)[2][2][4][2], const pg8::Unit& u, int wr, int wc, int fr, int fq) const {
;     ...
;                 const int lrow = u.pm * 256 + ai * 128 + wr * 64 + m * 16 + fr, grow = row_base + lrow;
;                 if (grow >= MREAL) continue;
;                 const float ri = ss_rinv(rowss[grow]);
; #pragma unroll
;                 for (int bj = 0; bj < 2; ++bj) {
;                     const int col0 = u.pn * 256 + bj * 128 + wc * 32 + 8 * fq;
;                     f32x4 v0 = acc[ai][bj][m][0] * ri, v1 = acc[ai][bj][m][1] * ri;
;                     if (MODE == 1) {
; #pragma unroll
;                         for (int i = 0; i < 4; ++i) { const float a = fmaxf(v0[i], 0.f), b = fmaxf(v1[i], 0.f); v0[i] = a * a; v1[i] = b * b; }
;                         u32x4 w; w.x = cvtpk(v0[0], v0[1]); w.y = cvtpk(v0[2], v0[3]); w.z = cvtpk(v1[0], v1[1]); w.w = cvtpk(v1[2], v1[3]);
;                         *(u32x4*)(O + (size_t)lrow * DFF + col0) = w;
.LBB0_2035:
	v_mbcnt_lo_u32_b32 v215, -1, 0
	v_mbcnt_hi_u32_b32 v215, -1, v215
	v_and_b32_e32 v214, 3, v215
	v_lshlrev_b32_e32 v214, 6, v214
	v_and_b32_e32 v155, 60, v215
	v_or_b32_e32 v214, v214, v155
	v_lshrrev_b32_e32 v155, 2, v215
	v_and_b32_e32 v156, 15, v215
	v_sub_u32_e32 v155, v155, v156
	v_lshlrev_b32_e32 v250, 13, v155
	v_and_b32_e32 v155, 3, v215
	v_lshrrev_b32_e32 v156, 4, v215
	v_sub_u32_e32 v155, v155, v156
	v_lshl_add_u32 v250, v155, 4, v250
	v_ashrrev_i32_e32 v251, 31, v250
	v_lshl_add_u32 v142, s38, 8, v158
	v_lshl_or_b32 v140, s36, 8, v160
	v_add_u32_e32 v144, s66, v142
	v_cmp_gt_i32_e32 vcc, s54, v144
	v_ashrrev_i32_e32 v145, 31, v144
	v_ashrrev_i32_e32 v141, 31, v140
	s_and_saveexec_b64 s[36:37], vcc
	s_cbranch_execz .LBB0_2037
	v_mov_b64_e32 v[146:147], v[230:231]
	v_ffbh_u32_e32 v143, v147
	v_min_u32_e32 v148, 32, v143
	v_lshlrev_b64 v[146:147], v148, v[146:147]
	v_min_u32_e32 v143, 1, v146
	v_or_b32_e32 v143, v147, v143
	v_cvt_f32_u32_e32 v146, v143
	v_sub_u32_e32 v147, 32, v148
	v_ashrrev_i32_e32 v143, 31, v142
	v_lshlrev_b64 v[148:149], 13, v[142:143]
	v_ldexp_f32 v146, v146, v147
	v_fmamk_f32 v146, v146, 0x30800000, v203
	v_rsq_f32_e32 v146, v146
	v_lshl_add_u64 v[148:149], s[8:9], 0, v[148:149]
	v_lshl_add_u64 v[148:149], v[140:141], 1, v[148:149]
	v_pk_mul_f32 v[128:129], v[128:129], v[146:147] op_sel_hi:[1,0]
	v_pk_mul_f32 v[126:127], v[126:127], v[146:147] op_sel_hi:[1,0]
	v_pk_mul_f32 v[124:125], v[124:125], v[146:147] op_sel_hi:[1,0]
	v_pk_mul_f32 v[122:123], v[122:123], v[146:147] op_sel_hi:[1,0]
	v_pk_mul_f32 v[120:121], v[120:121], v[146:147] op_sel_hi:[1,0]
	v_pk_mul_f32 v[118:119], v[118:119], v[146:147] op_sel_hi:[1,0]
	v_pk_mul_f32 v[116:117], v[116:117], v[146:147] op_sel_hi:[1,0]
	v_pk_mul_f32 v[114:115], v[114:115], v[146:147] op_sel_hi:[1,0]
	v_max_f32_e32 v126, 0, v126
	v_max_f32_e32 v122, 0, v122
	v_max_f32_e32 v127, 0, v127
	v_max_f32_e32 v123, 0, v123
	v_max_f32_e32 v128, 0, v128
	v_max_f32_e32 v124, 0, v124
	v_max_f32_e32 v129, 0, v129
	v_max_f32_e32 v125, 0, v125
	v_max_f32_e32 v118, 0, v118
	v_max_f32_e32 v114, 0, v114
	v_max_f32_e32 v119, 0, v119
	v_max_f32_e32 v115, 0, v115
	v_max_f32_e32 v120, 0, v120
	v_max_f32_e32 v116, 0, v116
	v_max_f32_e32 v121, 0, v121
	v_max_f32_e32 v117, 0, v117
	v_pk_mul_f32 v[126:127], v[126:127], v[126:127]
	v_pk_mul_f32 v[122:123], v[122:123], v[122:123]
	v_pk_mul_f32 v[128:129], v[128:129], v[128:129]
	v_pk_mul_f32 v[124:125], v[124:125], v[124:125]
	v_pk_mul_f32 v[118:119], v[118:119], v[118:119]
	v_pk_mul_f32 v[146:147], v[114:115], v[114:115]
	v_pk_mul_f32 v[120:121], v[120:121], v[120:121]
	v_pk_mul_f32 v[150:151], v[116:117], v[116:117]
	v_cvt_pk_bf16_f32 v114, v126, v127
	v_cvt_pk_bf16_f32 v115, v128, v129
	v_cvt_pk_bf16_f32 v116, v122, v123
	v_cvt_pk_bf16_f32 v117, v124, v125
	v_cvt_pk_bf16_f32 v118, v118, v119
	v_cvt_pk_bf16_f32 v119, v120, v121
	v_cvt_pk_bf16_f32 v120, v146, v147
	v_cvt_pk_bf16_f32 v121, v150, v151
	ds_bpermute_b32 v114, v214, v114
	ds_bpermute_b32 v115, v214, v115
	ds_bpermute_b32 v116, v214, v116
	ds_bpermute_b32 v117, v214, v117
	ds_bpermute_b32 v118, v214, v118
	ds_bpermute_b32 v119, v214, v119
	ds_bpermute_b32 v120, v214, v120
	ds_bpermute_b32 v121, v214, v121
	v_lshl_add_u64 v[252:253], v[250:251], 0, v[148:149]
	s_waitcnt lgkmcnt(0)
	global_store_dwordx4 v[252:253], v[114:117], off
	global_store_dwordx4 v[252:253], v[118:121], off offset:256
.LBB0_2037:
	s_or_b64 exec, exec, s[36:37]
	v_or_b32_e32 v114, 16, v142
	v_cmp_ge_i32_e32 vcc, s76, v114
	s_and_saveexec_b64 s[36:37], vcc
	s_cbranch_execz .LBB0_2039
	v_mov_b64_e32 v[116:117], v[232:233]
	v_ffbh_u32_e32 v115, v117
	v_min_u32_e32 v118, 32, v115
	v_lshlrev_b64 v[116:117], v118, v[116:117]
	v_min_u32_e32 v115, 1, v116
	v_or_b32_e32 v115, v117, v115
	v_cvt_f32_u32_e32 v116, v115
	v_sub_u32_e32 v117, 32, v118
	v_ashrrev_i32_e32 v115, 31, v114
	v_lshlrev_b64 v[114:115], 13, v[114:115]
	v_ldexp_f32 v116, v116, v117
	v_fmamk_f32 v116, v116, 0x30800000, v203
	v_rsq_f32_e32 v116, v116
	v_lshl_add_u64 v[114:115], s[8:9], 0, v[114:115]
	v_lshl_add_u64 v[114:115], v[140:141], 1, v[114:115]
	v_pk_mul_f32 v[112:113], v[112:113], v[116:117] op_sel_hi:[1,0]
	v_pk_mul_f32 v[110:111], v[110:111], v[116:117] op_sel_hi:[1,0]
	v_pk_mul_f32 v[108:109], v[108:109], v[116:117] op_sel_hi:[1,0]
	v_pk_mul_f32 v[106:107], v[106:107], v[116:117] op_sel_hi:[1,0]
	v_pk_mul_f32 v[104:105], v[104:105], v[116:117] op_sel_hi:[1,0]
	v_pk_mul_f32 v[102:103], v[102:103], v[116:117] op_sel_hi:[1,0]
	v_pk_mul_f32 v[100:101], v[100:101], v[116:117] op_sel_hi:[1,0]
	v_pk_mul_f32 v[98:99], v[98:99], v[116:117] op_sel_hi:[1,0]
	v_max_f32_e32 v110, 0, v110
	v_max_f32_e32 v106, 0, v106
	v_max_f32_e32 v111, 0, v111
	v_max_f32_e32 v107, 0, v107
	v_max_f32_e32 v112, 0, v112
	v_max_f32_e32 v108, 0, v108
	v_max_f32_e32 v113, 0, v113
	v_max_f32_e32 v109, 0, v109
	v_max_f32_e32 v102, 0, v102
	v_max_f32_e32 v98, 0, v98
	v_max_f32_e32 v103, 0, v103
	v_max_f32_e32 v99, 0, v99
	v_max_f32_e32 v104, 0, v104
	v_max_f32_e32 v100, 0, v100
	v_max_f32_e32 v105, 0, v105
	v_max_f32_e32 v101, 0, v101
	v_pk_mul_f32 v[110:111], v[110:111], v[110:111]
	v_pk_mul_f32 v[106:107], v[106:107], v[106:107]
	v_pk_mul_f32 v[112:113], v[112:113], v[112:113]
	v_pk_mul_f32 v[108:109], v[108:109], v[108:109]
	v_pk_mul_f32 v[102:103], v[102:103], v[102:103]
	v_pk_mul_f32 v[116:117], v[98:99], v[98:99]
	v_pk_mul_f32 v[104:105], v[104:105], v[104:105]
	v_pk_mul_f32 v[118:119], v[100:101], v[100:101]
	v_cvt_pk_bf16_f32 v98, v110, v111
	v_cvt_pk_bf16_f32 v99, v112, v113
	v_cvt_pk_bf16_f32 v100, v106, v107
	v_cvt_pk_bf16_f32 v101, v108, v109
	v_cvt_pk_bf16_f32 v102, v102, v103
	v_cvt_pk_bf16_f32 v103, v104, v105
	v_cvt_pk_bf16_f32 v104, v116, v117
	v_cvt_pk_bf16_f32 v105, v118, v119
	ds_bpermute_b32 v98, v214, v98
	ds_bpermute_b32 v99, v214, v99
	ds_bpermute_b32 v100, v214, v100
	ds_bpermute_b32 v101, v214, v101
	ds_bpermute_b32 v102, v214, v102
	ds_bpermute_b32 v103, v214, v103
	ds_bpermute_b32 v104, v214, v104
	ds_bpermute_b32 v105, v214, v105
	v_lshl_add_u64 v[252:253], v[250:251], 0, v[114:115]
	s_waitcnt lgkmcnt(0)
	global_store_dwordx4 v[252:253], v[98:101], off
	global_store_dwordx4 v[252:253], v[102:105], off offset:256
; __device__ __forceinline__ float ss_rinv(u64 v) { return __builtin_amdgcn_rsqf((float)v * SS_INV + 1e-6f); }
; __device__ __forceinline__ unsigned cvtpk(float lo, float hi) { f32x2 v = {lo, hi}; bf16x2_t b = __builtin_convertvector(v, bf16x2_t); return __builtin_bit_cast(unsigned, b); }
;     __device__ __forceinline__ void operator()(const f32x4 (&acc)[2][2][4][2], const pg8::Unit& u, int wr, int wc, int fr, int fq) const {
;     ...
;                 const int lrow = u.pm * 256 + ai * 128 + wr * 64 + m * 16 + fr, grow = row_base + lrow;
;                 if (grow >= MREAL) continue;
;                 const float ri = ss_rinv(rowss[grow]);
; #pragma unroll
;                 for (int bj = 0; bj < 2; ++bj) {
;                     const int col0 = u.pn * 256 + bj * 128 + wc * 32 + 8 * fq;
;                     f32x4 v0 = acc[ai][bj][m][0] * ri, v1 = acc[ai][bj][m][1] * ri;
;                     if (MODE == 1) {
; #pragma unroll
;                         for (int i = 0; i < 4; ++i) { const float a = fmaxf(v0[i], 0.f), b = fmaxf(v1[i], 0.f); v0[i] = a * a; v1[i] = b * b; }
;                         u32x4 w; w.x = cvtpk(v0[0], v0[1]); w.y = cvtpk(v0[2], v0[3]); w.z = cvtpk(v1[0], v1[1]); w.w = cvtpk(v1[2], v1[3]);
;                         *(u32x4*)(O + (size_t)lrow * DFF + col0) = w;
.LBB0_2039:
	s_or_b64 exec, exec, s[36:37]
	v_or_b32_e32 v98, 32, v142
	v_cmp_ge_i32_e32 vcc, s76, v98
	s_and_saveexec_b64 s[36:37], vcc
	s_cbranch_execz .LBB0_2041
	v_mov_b64_e32 v[100:101], v[234:235]
	v_ffbh_u32_e32 v99, v101
	v_min_u32_e32 v102, 32, v99
	v_lshlrev_b64 v[100:101], v102, v[100:101]
	v_min_u32_e32 v99, 1, v100
	v_or_b32_e32 v99, v101, v99
	v_cvt_f32_u32_e32 v100, v99
	v_sub_u32_e32 v101, 32, v102
	v_ashrrev_i32_e32 v99, 31, v98
	v_lshlrev_b64 v[98:99], 13, v[98:99]
	v_ldexp_f32 v100, v100, v101
	v_fmamk_f32 v100, v100, 0x30800000, v203
	v_rsq_f32_e32 v100, v100
	v_lshl_add_u64 v[98:99], s[8:9], 0, v[98:99]
	v_lshl_add_u64 v[98:99], v[140:141], 1, v[98:99]
	v_pk_mul_f32 v[96:97], v[96:97], v[100:101] op_sel_hi:[1,0]
	v_pk_mul_f32 v[94:95], v[94:95], v[100:101] op_sel_hi:[1,0]
	v_pk_mul_f32 v[92:93], v[92:93], v[100:101] op_sel_hi:[1,0]
	v_pk_mul_f32 v[90:91], v[90:91], v[100:101] op_sel_hi:[1,0]
	v_pk_mul_f32 v[88:89], v[88:89], v[100:101] op_sel_hi:[1,0]
	v_pk_mul_f32 v[86:87], v[86:87], v[100:101] op_sel_hi:[1,0]
	v_pk_mul_f32 v[84:85], v[84:85], v[100:101] op_sel_hi:[1,0]
	v_pk_mul_f32 v[82:83], v[82:83], v[100:101] op_sel_hi:[1,0]
	v_max_f32_e32 v94, 0, v94
	v_max_f32_e32 v90, 0, v90
	v_max_f32_e32 v95, 0, v95
	v_max_f32_e32 v91, 0, v91
	v_max_f32_e32 v96, 0, v96
	v_max_f32_e32 v92, 0, v92
	v_max_f32_e32 v97, 0, v97
	v_max_f32_e32 v93, 0, v93
	v_max_f32_e32 v86, 0, v86
	v_max_f32_e32 v82, 0, v82
	v_max_f32_e32 v87, 0, v87
	v_max_f32_e32 v83, 0, v83
	v_max_f32_e32 v88, 0, v88
	v_max_f32_e32 v84, 0, v84
	v_max_f32_e32 v89, 0, v89
	v_max_f32_e32 v85, 0, v85
	v_pk_mul_f32 v[94:95], v[94:95], v[94:95]
	v_pk_mul_f32 v[90:91], v[90:91], v[90:91]
	v_pk_mul_f32 v[96:97], v[96:97], v[96:97]
	v_pk_mul_f32 v[92:93], v[92:93], v[92:93]
	v_pk_mul_f32 v[86:87], v[86:87], v[86:87]
	v_pk_mul_f32 v[100:101], v[82:83], v[82:83]
	v_pk_mul_f32 v[88:89], v[88:89], v[88:89]
	v_pk_mul_f32 v[102:103], v[84:85], v[84:85]
	v_cvt_pk_bf16_f32 v82, v94, v95
	v_cvt_pk_bf16_f32 v83, v96, v97
	v_cvt_pk_bf16_f32 v84, v90, v91
	v_cvt_pk_bf16_f32 v85, v92, v93
	v_cvt_pk_bf16_f32 v86, v86, v87
	v_cvt_pk_bf16_f32 v87, v88, v89
	v_cvt_pk_bf16_f32 v88, v100, v101
	v_cvt_pk_bf16_f32 v89, v102, v103
	ds_bpermute_b32 v82, v214, v82
	ds_bpermute_b32 v83, v214, v83
	ds_bpermute_b32 v84, v214, v84
	ds_bpermute_b32 v85, v214, v85
	ds_bpermute_b32 v86, v214, v86
	ds_bpermute_b32 v87, v214, v87
	ds_bpermute_b32 v88, v214, v88
	ds_bpermute_b32 v89, v214, v89
	v_lshl_add_u64 v[252:253], v[250:251], 0, v[98:99]
	s_waitcnt lgkmcnt(0)
	global_store_dwordx4 v[252:253], v[82:85], off
	global_store_dwordx4 v[252:253], v[86:89], off offset:256
.LBB0_2041:
	s_or_b64 exec, exec, s[36:37]
	v_or_b32_e32 v82, 48, v142
	v_cmp_ge_i32_e32 vcc, s76, v82
	s_and_saveexec_b64 s[36:37], vcc
	s_cbranch_execz .LBB0_2043
	v_mov_b64_e32 v[84:85], v[236:237]
	v_ffbh_u32_e32 v83, v85
	v_min_u32_e32 v86, 32, v83
	v_lshlrev_b64 v[84:85], v86, v[84:85]
	v_min_u32_e32 v83, 1, v84
	v_or_b32_e32 v83, v85, v83
	v_cvt_f32_u32_e32 v84, v83
	v_sub_u32_e32 v85, 32, v86
	v_ashrrev_i32_e32 v83, 31, v82
	v_lshlrev_b64 v[82:83], 13, v[82:83]
	v_ldexp_f32 v84, v84, v85
	v_fmamk_f32 v84, v84, 0x30800000, v203
	v_rsq_f32_e32 v84, v84
	v_lshl_add_u64 v[82:83], s[8:9], 0, v[82:83]
	v_lshl_add_u64 v[82:83], v[140:141], 1, v[82:83]
	v_pk_mul_f32 v[80:81], v[80:81], v[84:85] op_sel_hi:[1,0]
	v_pk_mul_f32 v[78:79], v[78:79], v[84:85] op_sel_hi:[1,0]
	v_pk_mul_f32 v[76:77], v[76:77], v[84:85] op_sel_hi:[1,0]
	v_pk_mul_f32 v[74:75], v[74:75], v[84:85] op_sel_hi:[1,0]
	v_pk_mul_f32 v[72:73], v[72:73], v[84:85] op_sel_hi:[1,0]
	v_pk_mul_f32 v[70:71], v[70:71], v[84:85] op_sel_hi:[1,0]
	v_pk_mul_f32 v[68:69], v[68:69], v[84:85] op_sel_hi:[1,0]
	v_pk_mul_f32 v[66:67], v[66:67], v[84:85] op_sel_hi:[1,0]
	v_max_f32_e32 v78, 0, v78
	v_max_f32_e32 v74, 0, v74
	v_max_f32_e32 v79, 0, v79
	v_max_f32_e32 v75, 0, v75
	v_max_f32_e32 v80, 0, v80
	v_max_f32_e32 v76, 0, v76
	v_max_f32_e32 v81, 0, v81
	v_max_f32_e32 v77, 0, v77
	v_max_f32_e32 v70, 0, v70
	v_max_f32_e32 v66, 0, v66
	v_max_f32_e32 v71, 0, v71
	v_max_f32_e32 v67, 0, v67
	v_max_f32_e32 v72, 0, v72
	v_max_f32_e32 v68, 0, v68
	v_max_f32_e32 v73, 0, v73
	v_max_f32_e32 v69, 0, v69
	v_pk_mul_f32 v[78:79], v[78:79], v[78:79]
	v_pk_mul_f32 v[74:75], v[74:75], v[74:75]
	v_pk_mul_f32 v[80:81], v[80:81], v[80:81]
	v_pk_mul_f32 v[76:77], v[76:77], v[76:77]
	v_pk_mul_f32 v[70:71], v[70:71], v[70:71]
	v_pk_mul_f32 v[84:85], v[66:67], v[66:67]
	v_pk_mul_f32 v[72:73], v[72:73], v[72:73]
	v_pk_mul_f32 v[86:87], v[68:69], v[68:69]
	v_cvt_pk_bf16_f32 v66, v78, v79
	v_cvt_pk_bf16_f32 v67, v80, v81
	v_cvt_pk_bf16_f32 v68, v74, v75
	v_cvt_pk_bf16_f32 v69, v76, v77
	v_cvt_pk_bf16_f32 v70, v70, v71
	v_cvt_pk_bf16_f32 v71, v72, v73
	v_cvt_pk_bf16_f32 v72, v84, v85
	v_cvt_pk_bf16_f32 v73, v86, v87
	ds_bpermute_b32 v66, v214, v66
	ds_bpermute_b32 v67, v214, v67
	ds_bpermute_b32 v68, v214, v68
	ds_bpermute_b32 v69, v214, v69
	ds_bpermute_b32 v70, v214, v70
	ds_bpermute_b32 v71, v214, v71
	ds_bpermute_b32 v72, v214, v72
	ds_bpermute_b32 v73, v214, v73
	v_lshl_add_u64 v[252:253], v[250:251], 0, v[82:83]
	s_waitcnt lgkmcnt(0)
	global_store_dwordx4 v[252:253], v[66:69], off
	global_store_dwordx4 v[252:253], v[70:73], off offset:256
; __device__ __forceinline__ float ss_rinv(u64 v) { return __builtin_amdgcn_rsqf((float)v * SS_INV + 1e-6f); }
; __device__ __forceinline__ unsigned cvtpk(float lo, float hi) { f32x2 v = {lo, hi}; bf16x2_t b = __builtin_convertvector(v, bf16x2_t); return __builtin_bit_cast(unsigned, b); }
;     __device__ __forceinline__ void operator()(const f32x4 (&acc)[2][2][4][2], const pg8::Unit& u, int wr, int wc, int fr, int fq) const {
;     ...
;                 const int lrow = u.pm * 256 + ai * 128 + wr * 64 + m * 16 + fr, grow = row_base + lrow;
;                 if (grow >= MREAL) continue;
;                 const float ri = ss_rinv(rowss[grow]);
; #pragma unroll
;                 for (int bj = 0; bj < 2; ++bj) {
;                     const int col0 = u.pn * 256 + bj * 128 + wc * 32 + 8 * fq;
;                     f32x4 v0 = acc[ai][bj][m][0] * ri, v1 = acc[ai][bj][m][1] * ri;
;                     if (MODE == 1) {
; #pragma unroll
;                         for (int i = 0; i < 4; ++i) { const float a = fmaxf(v0[i], 0.f), b = fmaxf(v1[i], 0.f); v0[i] = a * a; v1[i] = b * b; }
;                         u32x4 w; w.x = cvtpk(v0[0], v0[1]); w.y = cvtpk(v0[2], v0[3]); w.z = cvtpk(v1[0], v1[1]); w.w = cvtpk(v1[2], v1[3]);
;                         *(u32x4*)(O + (size_t)lrow * DFF + col0) = w;
.LBB0_2043:
	s_or_b64 exec, exec, s[36:37]
	v_add_u32_e32 v66, 0x80, v142
	v_add_u32_e32 v68, s66, v66
	v_cmp_gt_i32_e32 vcc, s54, v68
	s_and_saveexec_b64 s[36:37], vcc
	s_cbranch_execz .LBB0_2045
	v_mov_b64_e32 v[68:69], v[238:239]
	v_ffbh_u32_e32 v67, v69
	v_min_u32_e32 v70, 32, v67
	v_lshlrev_b64 v[68:69], v70, v[68:69]
	v_min_u32_e32 v67, 1, v68
	v_or_b32_e32 v67, v69, v67
	v_cvt_f32_u32_e32 v68, v67
	v_sub_u32_e32 v69, 32, v70
	v_ashrrev_i32_e32 v67, 31, v66
	v_lshlrev_b64 v[66:67], 13, v[66:67]
	v_ldexp_f32 v68, v68, v69
	v_fmamk_f32 v68, v68, 0x30800000, v203
	v_rsq_f32_e32 v68, v68
	v_lshl_add_u64 v[66:67], s[8:9], 0, v[66:67]
	v_lshl_add_u64 v[66:67], v[140:141], 1, v[66:67]
	v_pk_mul_f32 v[64:65], v[64:65], v[68:69] op_sel_hi:[1,0]
	v_pk_mul_f32 v[62:63], v[62:63], v[68:69] op_sel_hi:[1,0]
	v_pk_mul_f32 v[60:61], v[60:61], v[68:69] op_sel_hi:[1,0]
	v_pk_mul_f32 v[58:59], v[58:59], v[68:69] op_sel_hi:[1,0]
	v_pk_mul_f32 v[56:57], v[56:57], v[68:69] op_sel_hi:[1,0]
	v_pk_mul_f32 v[54:55], v[54:55], v[68:69] op_sel_hi:[1,0]
	v_pk_mul_f32 v[52:53], v[52:53], v[68:69] op_sel_hi:[1,0]
	v_pk_mul_f32 v[50:51], v[50:51], v[68:69] op_sel_hi:[1,0]
	v_max_f32_e32 v62, 0, v62
	v_max_f32_e32 v58, 0, v58
	v_max_f32_e32 v63, 0, v63
	v_max_f32_e32 v59, 0, v59
	v_max_f32_e32 v64, 0, v64
	v_max_f32_e32 v60, 0, v60
	v_max_f32_e32 v65, 0, v65
	v_max_f32_e32 v61, 0, v61
	v_max_f32_e32 v54, 0, v54
	v_max_f32_e32 v50, 0, v50
	v_max_f32_e32 v55, 0, v55
	v_max_f32_e32 v51, 0, v51
	v_max_f32_e32 v56, 0, v56
	v_max_f32_e32 v52, 0, v52
	v_max_f32_e32 v57, 0, v57
	v_max_f32_e32 v53, 0, v53
	v_pk_mul_f32 v[62:63], v[62:63], v[62:63]
	v_pk_mul_f32 v[58:59], v[58:59], v[58:59]
	v_pk_mul_f32 v[64:65], v[64:65], v[64:65]
	v_pk_mul_f32 v[60:61], v[60:61], v[60:61]
	v_pk_mul_f32 v[54:55], v[54:55], v[54:55]
	v_pk_mul_f32 v[68:69], v[50:51], v[50:51]
	v_pk_mul_f32 v[56:57], v[56:57], v[56:57]
	v_pk_mul_f32 v[70:71], v[52:53], v[52:53]
	v_cvt_pk_bf16_f32 v50, v62, v63
	v_cvt_pk_bf16_f32 v51, v64, v65
	v_cvt_pk_bf16_f32 v52, v58, v59
	v_cvt_pk_bf16_f32 v53, v60, v61
	v_cvt_pk_bf16_f32 v54, v54, v55
	v_cvt_pk_bf16_f32 v55, v56, v57
	v_cvt_pk_bf16_f32 v56, v68, v69
	v_cvt_pk_bf16_f32 v57, v70, v71
	ds_bpermute_b32 v50, v214, v50
	ds_bpermute_b32 v51, v214, v51
	ds_bpermute_b32 v52, v214, v52
	ds_bpermute_b32 v53, v214, v53
	ds_bpermute_b32 v54, v214, v54
	ds_bpermute_b32 v55, v214, v55
	ds_bpermute_b32 v56, v214, v56
	ds_bpermute_b32 v57, v214, v57
	v_lshl_add_u64 v[252:253], v[250:251], 0, v[66:67]
	s_waitcnt lgkmcnt(0)
	global_store_dwordx4 v[252:253], v[50:53], off
	global_store_dwordx4 v[252:253], v[54:57], off offset:256
.LBB0_2045:
	s_or_b64 exec, exec, s[36:37]
	v_add_u32_e32 v50, 0x90, v142
	v_add_u32_e32 v52, s66, v50
	v_cmp_gt_i32_e32 vcc, s54, v52
	s_and_saveexec_b64 s[36:37], vcc
	s_cbranch_execz .LBB0_2047
	v_mov_b64_e32 v[52:53], v[240:241]
	v_ffbh_u32_e32 v51, v53
	v_min_u32_e32 v54, 32, v51
	v_lshlrev_b64 v[52:53], v54, v[52:53]
	v_min_u32_e32 v51, 1, v52
	v_or_b32_e32 v51, v53, v51
	v_cvt_f32_u32_e32 v52, v51
	v_sub_u32_e32 v53, 32, v54
	v_ashrrev_i32_e32 v51, 31, v50
	v_lshlrev_b64 v[50:51], 13, v[50:51]
	v_ldexp_f32 v52, v52, v53
	v_fmamk_f32 v52, v52, 0x30800000, v203
	v_rsq_f32_e32 v52, v52
	v_lshl_add_u64 v[50:51], s[8:9], 0, v[50:51]
	v_lshl_add_u64 v[50:51], v[140:141], 1, v[50:51]
	v_pk_mul_f32 v[48:49], v[48:49], v[52:53] op_sel_hi:[1,0]
	v_pk_mul_f32 v[46:47], v[46:47], v[52:53] op_sel_hi:[1,0]
	v_pk_mul_f32 v[44:45], v[44:45], v[52:53] op_sel_hi:[1,0]
	v_pk_mul_f32 v[42:43], v[42:43], v[52:53] op_sel_hi:[1,0]
	v_pk_mul_f32 v[40:41], v[40:41], v[52:53] op_sel_hi:[1,0]
	v_pk_mul_f32 v[38:39], v[38:39], v[52:53] op_sel_hi:[1,0]
	v_pk_mul_f32 v[36:37], v[36:37], v[52:53] op_sel_hi:[1,0]
	v_pk_mul_f32 v[34:35], v[34:35], v[52:53] op_sel_hi:[1,0]
	v_max_f32_e32 v46, 0, v46
	v_max_f32_e32 v42, 0, v42
	v_max_f32_e32 v47, 0, v47
	v_max_f32_e32 v43, 0, v43
	v_max_f32_e32 v48, 0, v48
	v_max_f32_e32 v44, 0, v44
	v_max_f32_e32 v49, 0, v49
	v_max_f32_e32 v45, 0, v45
	v_max_f32_e32 v38, 0, v38
	v_max_f32_e32 v34, 0, v34
	v_max_f32_e32 v39, 0, v39
	v_max_f32_e32 v35, 0, v35
	v_max_f32_e32 v40, 0, v40
	v_max_f32_e32 v36, 0, v36
	v_max_f32_e32 v41, 0, v41
	v_max_f32_e32 v37, 0, v37
	v_pk_mul_f32 v[46:47], v[46:47], v[46:47]
	v_pk_mul_f32 v[42:43], v[42:43], v[42:43]
	v_pk_mul_f32 v[48:49], v[48:49], v[48:49]
	v_pk_mul_f32 v[44:45], v[44:45], v[44:45]
	v_pk_mul_f32 v[38:39], v[38:39], v[38:39]
	v_pk_mul_f32 v[52:53], v[34:35], v[34:35]
	v_pk_mul_f32 v[40:41], v[40:41], v[40:41]
	v_pk_mul_f32 v[54:55], v[36:37], v[36:37]
	v_cvt_pk_bf16_f32 v34, v46, v47
	v_cvt_pk_bf16_f32 v35, v48, v49
	v_cvt_pk_bf16_f32 v36, v42, v43
	v_cvt_pk_bf16_f32 v37, v44, v45
	v_cvt_pk_bf16_f32 v38, v38, v39
	v_cvt_pk_bf16_f32 v39, v40, v41
	v_cvt_pk_bf16_f32 v40, v52, v53
	v_cvt_pk_bf16_f32 v41, v54, v55
	ds_bpermute_b32 v34, v214, v34
	ds_bpermute_b32 v35, v214, v35
	ds_bpermute_b32 v36, v214, v36
	ds_bpermute_b32 v37, v214, v37
	ds_bpermute_b32 v38, v214, v38
	ds_bpermute_b32 v39, v214, v39
	ds_bpermute_b32 v40, v214, v40
	ds_bpermute_b32 v41, v214, v41
	v_lshl_add_u64 v[252:253], v[250:251], 0, v[50:51]
	s_waitcnt lgkmcnt(0)
	global_store_dwordx4 v[252:253], v[34:37], off
	global_store_dwordx4 v[252:253], v[38:41], off offset:256
; __device__ __forceinline__ float ss_rinv(u64 v) { return __builtin_amdgcn_rsqf((float)v * SS_INV + 1e-6f); }
; __device__ __forceinline__ unsigned cvtpk(float lo, float hi) { f32x2 v = {lo, hi}; bf16x2_t b = __builtin_convertvector(v, bf16x2_t); return __builtin_bit_cast(unsigned, b); }
;     __device__ __forceinline__ void operator()(const f32x4 (&acc)[2][2][4][2], const pg8::Unit& u, int wr, int wc, int fr, int fq) const {
;     ...
;                 const int lrow = u.pm * 256 + ai * 128 + wr * 64 + m * 16 + fr, grow = row_base + lrow;
;                 if (grow >= MREAL) continue;
;                 const float ri = ss_rinv(rowss[grow]);
; #pragma unroll
;                 for (int bj = 0; bj < 2; ++bj) {
;                     const int col0 = u.pn * 256 + bj * 128 + wc * 32 + 8 * fq;
;                     f32x4 v0 = acc[ai][bj][m][0] * ri, v1 = acc[ai][bj][m][1] * ri;
;                     if (MODE == 1) {
; #pragma unroll
;                         for (int i = 0; i < 4; ++i) { const float a = fmaxf(v0[i], 0.f), b = fmaxf(v1[i], 0.f); v0[i] = a * a; v1[i] = b * b; }
;                         u32x4 w; w.x = cvtpk(v0[0], v0[1]); w.y = cvtpk(v0[2], v0[3]); w.z = cvtpk(v1[0], v1[1]); w.w = cvtpk(v1[2], v1[3]);
;                         *(u32x4*)(O + (size_t)lrow * DFF + col0) = w;
.LBB0_2047:
	s_or_b64 exec, exec, s[36:37]
	v_add_u32_e32 v34, 0xa0, v142
	v_add_u32_e32 v36, s66, v34
	v_cmp_gt_i32_e32 vcc, s54, v36
	s_and_saveexec_b64 s[36:37], vcc
	s_cbranch_execz .LBB0_2049
	v_mov_b64_e32 v[36:37], v[242:243]
	v_ffbh_u32_e32 v35, v37
	v_min_u32_e32 v38, 32, v35
	v_lshlrev_b64 v[36:37], v38, v[36:37]
	v_min_u32_e32 v35, 1, v36
	v_or_b32_e32 v35, v37, v35
	v_cvt_f32_u32_e32 v36, v35
	v_sub_u32_e32 v37, 32, v38
	v_ashrrev_i32_e32 v35, 31, v34
	v_lshlrev_b64 v[34:35], 13, v[34:35]
	v_ldexp_f32 v36, v36, v37
	v_fmamk_f32 v36, v36, 0x30800000, v203
	v_rsq_f32_e32 v36, v36
	v_lshl_add_u64 v[34:35], s[8:9], 0, v[34:35]
	v_lshl_add_u64 v[34:35], v[140:141], 1, v[34:35]
	v_pk_mul_f32 v[30:31], v[30:31], v[36:37] op_sel_hi:[1,0]
	v_pk_mul_f32 v[28:29], v[28:29], v[36:37] op_sel_hi:[1,0]
	v_pk_mul_f32 v[26:27], v[26:27], v[36:37] op_sel_hi:[1,0]
	v_pk_mul_f32 v[24:25], v[24:25], v[36:37] op_sel_hi:[1,0]
	v_pk_mul_f32 v[22:23], v[22:23], v[36:37] op_sel_hi:[1,0]
	v_pk_mul_f32 v[20:21], v[20:21], v[36:37] op_sel_hi:[1,0]
	v_pk_mul_f32 v[18:19], v[18:19], v[36:37] op_sel_hi:[1,0]
	v_pk_mul_f32 v[16:17], v[16:17], v[36:37] op_sel_hi:[1,0]
	v_max_f32_e32 v28, 0, v28
	v_max_f32_e32 v24, 0, v24
	v_max_f32_e32 v29, 0, v29
	v_max_f32_e32 v25, 0, v25
	v_max_f32_e32 v30, 0, v30
	v_max_f32_e32 v26, 0, v26
	v_max_f32_e32 v31, 0, v31
	v_max_f32_e32 v27, 0, v27
	v_max_f32_e32 v20, 0, v20
	v_max_f32_e32 v16, 0, v16
	v_max_f32_e32 v21, 0, v21
	v_max_f32_e32 v17, 0, v17
	v_max_f32_e32 v22, 0, v22
	v_max_f32_e32 v18, 0, v18
	v_max_f32_e32 v23, 0, v23
	v_max_f32_e32 v19, 0, v19
	v_pk_mul_f32 v[28:29], v[28:29], v[28:29]
	v_pk_mul_f32 v[24:25], v[24:25], v[24:25]
	v_pk_mul_f32 v[30:31], v[30:31], v[30:31]
	v_pk_mul_f32 v[26:27], v[26:27], v[26:27]
	v_pk_mul_f32 v[20:21], v[20:21], v[20:21]
	v_pk_mul_f32 v[36:37], v[16:17], v[16:17]
	v_pk_mul_f32 v[22:23], v[22:23], v[22:23]
	v_pk_mul_f32 v[38:39], v[18:19], v[18:19]
	v_cvt_pk_bf16_f32 v16, v28, v29
	v_cvt_pk_bf16_f32 v17, v30, v31
	v_cvt_pk_bf16_f32 v18, v24, v25
	v_cvt_pk_bf16_f32 v19, v26, v27
	v_cvt_pk_bf16_f32 v20, v20, v21
	v_cvt_pk_bf16_f32 v21, v22, v23
	v_cvt_pk_bf16_f32 v22, v36, v37
	v_cvt_pk_bf16_f32 v23, v38, v39
	ds_bpermute_b32 v16, v214, v16
	ds_bpermute_b32 v17, v214, v17
	ds_bpermute_b32 v18, v214, v18
	ds_bpermute_b32 v19, v214, v19
	ds_bpermute_b32 v20, v214, v20
	ds_bpermute_b32 v21, v214, v21
	ds_bpermute_b32 v22, v214, v22
	ds_bpermute_b32 v23, v214, v23
	v_lshl_add_u64 v[252:253], v[250:251], 0, v[34:35]
	s_waitcnt lgkmcnt(0)
	global_store_dwordx4 v[252:253], v[16:19], off
	global_store_dwordx4 v[252:253], v[20:23], off offset:256
.LBB0_2049:
	s_or_b64 exec, exec, s[36:37]
	v_add_u32_e32 v16, 0xb0, v142
	v_add_u32_e32 v18, s66, v16
	v_cmp_gt_i32_e32 vcc, s54, v18
	s_and_saveexec_b64 s[36:37], vcc
	s_cbranch_execz .LBB0_2051
	v_mov_b64_e32 v[18:19], v[244:245]
	v_ffbh_u32_e32 v17, v19
	v_min_u32_e32 v20, 32, v17
	v_lshlrev_b64 v[18:19], v20, v[18:19]
	v_min_u32_e32 v17, 1, v18
	v_or_b32_e32 v17, v19, v17
	v_cvt_f32_u32_e32 v18, v17
	v_sub_u32_e32 v19, 32, v20
	v_ashrrev_i32_e32 v17, 31, v16
	v_lshlrev_b64 v[16:17], 13, v[16:17]
	v_ldexp_f32 v18, v18, v19
	v_fmamk_f32 v18, v18, 0x30800000, v203
	v_rsq_f32_e32 v18, v18
	v_lshl_add_u64 v[16:17], s[8:9], 0, v[16:17]
	v_lshl_add_u64 v[16:17], v[140:141], 1, v[16:17]
	v_pk_mul_f32 v[14:15], v[14:15], v[18:19] op_sel_hi:[1,0]
	v_pk_mul_f32 v[12:13], v[12:13], v[18:19] op_sel_hi:[1,0]
	v_pk_mul_f32 v[10:11], v[10:11], v[18:19] op_sel_hi:[1,0]
	v_pk_mul_f32 v[8:9], v[8:9], v[18:19] op_sel_hi:[1,0]
	v_pk_mul_f32 v[6:7], v[6:7], v[18:19] op_sel_hi:[1,0]
	v_pk_mul_f32 v[4:5], v[4:5], v[18:19] op_sel_hi:[1,0]
	v_pk_mul_f32 v[2:3], v[2:3], v[18:19] op_sel_hi:[1,0]
	v_pk_mul_f32 v[0:1], v[0:1], v[18:19] op_sel_hi:[1,0]
	v_max_f32_e32 v12, 0, v12
	v_max_f32_e32 v8, 0, v8
	v_max_f32_e32 v13, 0, v13
	v_max_f32_e32 v9, 0, v9
	v_max_f32_e32 v14, 0, v14
	v_max_f32_e32 v10, 0, v10
	v_max_f32_e32 v15, 0, v15
	v_max_f32_e32 v11, 0, v11
	v_max_f32_e32 v4, 0, v4
	v_max_f32_e32 v0, 0, v0
	v_max_f32_e32 v5, 0, v5
	v_max_f32_e32 v1, 0, v1
	v_max_f32_e32 v6, 0, v6
	v_max_f32_e32 v2, 0, v2
	v_max_f32_e32 v7, 0, v7
	v_max_f32_e32 v3, 0, v3
	v_pk_mul_f32 v[12:13], v[12:13], v[12:13]
	v_pk_mul_f32 v[8:9], v[8:9], v[8:9]
	v_pk_mul_f32 v[14:15], v[14:15], v[14:15]
	v_pk_mul_f32 v[10:11], v[10:11], v[10:11]
	v_pk_mul_f32 v[4:5], v[4:5], v[4:5]
	v_pk_mul_f32 v[18:19], v[0:1], v[0:1]
	v_pk_mul_f32 v[6:7], v[6:7], v[6:7]
	v_pk_mul_f32 v[20:21], v[2:3], v[2:3]
	v_cvt_pk_bf16_f32 v0, v12, v13
	v_cvt_pk_bf16_f32 v1, v14, v15
	v_cvt_pk_bf16_f32 v2, v8, v9
	v_cvt_pk_bf16_f32 v3, v10, v11
	v_cvt_pk_bf16_f32 v4, v4, v5
	v_cvt_pk_bf16_f32 v5, v6, v7
	v_cvt_pk_bf16_f32 v6, v18, v19
	v_cvt_pk_bf16_f32 v7, v20, v21
	ds_bpermute_b32 v0, v214, v0
	ds_bpermute_b32 v1, v214, v1
	ds_bpermute_b32 v2, v214, v2
	ds_bpermute_b32 v3, v214, v3
	ds_bpermute_b32 v4, v214, v4
	ds_bpermute_b32 v5, v214, v5
	ds_bpermute_b32 v6, v214, v6
	ds_bpermute_b32 v7, v214, v7
	v_lshl_add_u64 v[252:253], v[250:251], 0, v[16:17]
	s_waitcnt lgkmcnt(0)
	global_store_dwordx4 v[252:253], v[0:3], off
	global_store_dwordx4 v[252:253], v[4:7], off offset:256
